# S5 scan items: batched operand loads and LDS reads; attention quad-max moved to rescale path
# speedup vs baseline: 1.0138x; 1.0138x over previous
; #define MFMA16(a, b, c) __builtin_amdgcn_mfma_f32_16x16x32_bf16((a), (b), (c), 0, 0, 0)
; DI unsigned pack2(float a, float b) { f2_t v = {a, b}; return __builtin_bit_cast(unsigned, __builtin_convertvector(v, bf2_t)); }
; DI float bf2f(bf16_t h) { return __uint_as_float(((unsigned)h) << 16); }
; template <bool FINAL>
; DI void s5_item(const Params& p, int layer, int item, char* lds) {
;     ...
;     const bf16_t* bt = p.s5bt + (size_t)(layer * 32 + g) * 128 * 32;
; #pragma unroll
;     for (int nt = 0; nt < 8; ++nt) bbf[nt] = *(const bf16x8*)(bt + (nt * 16 + c16) * 32 + quad * 8);
;   }
;   const float* par = p.s5par + (size_t)((layer * 32 + g) * 36) * 64 + lane;
;   const float are = par[0], aim = par[64];
;   float xr = 0.f, xi = 0.f;
;   float* stp = p.s5st + ((size_t)((b * 32 + g) * 128)) * 128 + lane;
;   bf16x8 cf[FINAL ? 4 : 1];
;   float dsk = 0.f;
;   if constexpr (FINAL) {
;     xr = stp[c * 128]; xi = stp[c * 128 + 64];
;     const float* cr = p.s5_cre + (size_t)((layer * 32 + g) * 16 + c16) * 64;
;     const float* ci = p.s5_cim + (size_t)((layer * 32 + g) * 16 + c16) * 64;
; #pragma unroll
;     for (int ks = 0; ks < 4; ++ks) {
;       const float* src = ((ks < 2) ? cr : ci) + (ks & 1) * 32 + quad * 8;
;       const float sg = (ks < 2) ? 1.f : -1.f;
;       const float4 v0 = *(const float4*)src, v1 = *(const float4*)(src + 4);
;       union { unsigned u[4]; bf16x8 v; } pk;
;       pk.u[0] = pack2(sg * v0.x, sg * v0.y); pk.u[1] = pack2(sg * v0.z, sg * v0.w);
;       pk.u[2] = pack2(sg * v1.x, sg * v1.y); pk.u[3] = pack2(sg * v1.z, sg * v1.w);
;       cf[ks] = pk.v;
;     }
;     dsk = p.s5_d[(layer * 32 + g) * 16 + c16];
;   }
;   for (int sc = 0; sc < 4; ++sc) {
;     const int tb = tok0 + sc * 16;
;     bf16x8 uf = bf16x8{0, 0, 0, 0, 0, 0, 0, 0};
;     if (quad < 2) uf = *(const bf16x8*)(p.proj + (size_t)(tb + c16) * PW + C_AU + g * 16 + quad * 8);
;     float uo[FINAL ? 4 : 1];
;     if constexpr (FINAL) {
; #pragma unroll
;       for (int r = 0; r < 4; ++r) uo[r] = bf2f(p.proj[(size_t)(tb + quad * 4 + r) * PW + C_AU + g * 16 + c16]);
;     }
; #pragma unroll
;     for (int nt = 0; nt < 8; ++nt) {
;       f32x4 acc = MFMA16(uf, bbf[nt], (f32x4{0.f, 0.f, 0.f, 0.f}));
; #pragma unroll
;       for (int r = 0; r < 4; ++r) bu[(quad * 4 + r) * 128 + nt * 16 + c16] = acc[r];
.LBB0_1065:
	s_or_b64 exec, exec, s[0:1]
	v_mov_b32_e32 v0, s3
	s_waitcnt lgkmcnt(0)
	s_barrier
	ds_read_b32 v0, v0
	s_movk_i32 s0, 0x13ff
	s_waitcnt lgkmcnt(0)
	v_cmp_lt_i32_e32 vcc, s0, v0
	v_readfirstlane_b32 s5, v0
	s_mov_b64 s[0:1], -1
	s_cbranch_vccnz .LBB0_1060
	s_cmpk_gt_i32 s5, 0x3ff
	s_cbranch_scc0 .LBB0_1076
	s_add_i32 s0, s5, 0xfffffc00
	v_mov_b32_e32 v34, v172
	s_lshl_b32 s1, s0, 2
	s_and_b32 s1, s1, 28
	v_ashrrev_i32_e32 v41, 6, v34
	v_add_u32_e32 v140, s1, v41
	v_add_u32_e32 v36, s97, v140
	v_ashrrev_i32_e32 v37, 31, v36
	v_readlane_b32 s80, v230, 42
	v_lshlrev_b64 v[2:3], 13, v[36:37]
	v_readlane_b32 s94, v230, 56
	v_readlane_b32 s95, v230, 57
	v_and_b32_e32 v40, 15, v34
	v_and_b32_e32 v0, 48, v34
	v_lshl_add_u64 v[2:3], s[94:95], 0, v[2:3]
	v_lshl_add_u64 v[2:3], v[2:3], 0, v[0:1]
	v_lshlrev_b32_e32 v0, 6, v40
	v_lshl_add_u64 v[2:3], v[2:3], 0, v[0:1]
	s_movk_i32 s1, 0x1000
	v_mul_lo_u32 v36, v36, 36
	global_load_dwordx4 v[30:33], v[2:3], off
	global_load_dwordx4 v[26:29], v[2:3], off offset:1024
	global_load_dwordx4 v[22:25], v[2:3], off offset:2048
	global_load_dwordx4 v[18:21], v[2:3], off offset:3072
	v_add_co_u32_e32 v2, vcc, s1, v2
	v_ashrrev_i32_e32 v37, 31, v36
	v_and_b32_e32 v35, 63, v34
	v_readlane_b32 s86, v230, 48
	v_readlane_b32 s87, v230, 49
	v_addc_co_u32_e32 v3, vcc, 0, v3, vcc
	v_lshlrev_b64 v[36:37], 8, v[36:37]
	global_load_dwordx4 v[14:17], v[2:3], off
	global_load_dwordx4 v[10:13], v[2:3], off offset:1024
	global_load_dwordx4 v[6:9], v[2:3], off offset:2048
	s_nop 0
	global_load_dwordx4 v[2:5], v[2:3], off offset:3072
	v_lshl_add_u64 v[36:37], s[86:87], 0, v[36:37]
	v_lshlrev_b32_e32 v0, 2, v35
	v_lshl_add_u64 v[36:37], v[36:37], 0, v[0:1]
	global_load_dword v141, v[36:37], off
	global_load_dword v142, v[36:37], off offset:256
	s_bfe_u32 s23, s5, 0x70003
	s_lshr_b32 s24, s0, 10
	s_lshl_b32 s1, s23, 6
	s_lshl_b32 s0, s24, 13
	v_bfe_u32 v42, v34, 4, 2
	s_or_b32 s6, s1, s0
	v_lshlrev_b32_e32 v36, 3, v42
	v_or_b32_e32 v37, s6, v40
	v_lshlrev_b32_e32 v84, 4, v140
	s_movk_i32 s6, 0x1200
	v_cmp_gt_u32_e64 s[0:1], 32, v35
	v_ashrrev_i32_e32 v85, 31, v84
	v_mov_b32_e32 v34, 0
	v_mul_lo_u32 v94, v37, s6
	v_lshlrev_b32_e32 v90, 1, v36
	v_mov_b32_e32 v36, 0
	v_mov_b32_e32 v37, 0
	v_mov_b32_e32 v38, 0
	v_mov_b32_e32 v39, 0
	v_readlane_b32 s81, v230, 43
	v_readlane_b32 s82, v230, 44
	v_readlane_b32 s83, v230, 45
	v_readlane_b32 s84, v230, 46
	v_readlane_b32 s85, v230, 47
	v_readlane_b32 s88, v230, 50
	v_readlane_b32 s89, v230, 51
	v_readlane_b32 s90, v230, 52
	v_readlane_b32 s91, v230, 53
	v_readlane_b32 s92, v230, 54
	v_readlane_b32 s93, v230, 55
	v_mov_b32_e32 v232, 0
	v_mov_b32_e32 v233, 0
	v_mov_b32_e32 v234, 0
	v_mov_b32_e32 v235, 0
	v_mov_b32_e32 v236, 0
	v_mov_b32_e32 v237, 0
	v_mov_b32_e32 v238, 0
	v_mov_b32_e32 v239, 0
	v_mov_b32_e32 v240, 0
	v_mov_b32_e32 v241, 0
	v_mov_b32_e32 v242, 0
	v_mov_b32_e32 v243, 0
	s_and_saveexec_b64 s[6:7], s[0:1]
	s_cbranch_execz .LBB0_1069
	v_mov_b32_e32 v95, v1
	v_lshl_add_u64 v[36:37], v[94:95], 1, s[78:79]
	v_lshl_add_u64 v[36:37], v[84:85], 1, v[36:37]
	v_mov_b32_e32 v91, v1
	v_lshl_add_u64 v[36:37], v[36:37], 0, v[90:91]
	v_add_co_u32_e32 v232, vcc, 0x24000, v36
	s_nop 1
	v_addc_co_u32_e32 v233, vcc, 0, v37, vcc
	v_add_co_u32_e32 v236, vcc, 0x48000, v36
	s_nop 1
	v_addc_co_u32_e32 v237, vcc, 0, v37, vcc
	v_add_co_u32_e32 v240, vcc, 0x6c000, v36
	s_nop 1
	v_addc_co_u32_e32 v241, vcc, 0, v37, vcc
	global_load_dwordx4 v[36:39], v[36:37], off
	global_load_dwordx4 v[232:235], v[232:233], off
	global_load_dwordx4 v[236:239], v[236:237], off
	global_load_dwordx4 v[240:243], v[240:241], off
.LBB0_1069:
	s_or_b64 exec, exec, s[6:7]
	s_waitcnt vmcnt(3)
	v_mfma_f32_16x16x32_bf16 v[44:47], v[36:39], v[30:33], 0
	v_lshl_add_u32 v52, v41, 14, 16
	v_lshlrev_b32_e32 v53, 11, v42
	v_lshlrev_b32_e32 v54, 2, v40
	v_mfma_f32_16x16x32_bf16 v[48:51], v[36:39], v[26:29], 0
	v_add3_u32 v144, v52, v53, v54
	v_lshl_add_u32 v143, v35, 2, v52
	v_add_u32_e32 v145, 0x400, v144
	v_mfma_f32_16x16x32_bf16 v[40:43], v[36:39], v[22:25], 0
	v_mov_b32_e32 v35, 0
	s_nop 2
	ds_write2_b32 v144, v44, v48 offset1:16
	ds_write2_b32 v144, v45, v49 offset0:128 offset1:144
	v_mfma_f32_16x16x32_bf16 v[52:55], v[36:39], v[18:21], 0
	ds_write2_b32 v145, v46, v50 offset1:16
	ds_write2_b32 v145, v47, v51 offset0:128 offset1:144
	s_nop 5
	ds_write2_b32 v144, v40, v52 offset0:32 offset1:48
	ds_write2_b32 v144, v41, v53 offset0:160 offset1:176
	v_mfma_f32_16x16x32_bf16 v[56:59], v[36:39], v[14:17], 0
	v_mfma_f32_16x16x32_bf16 v[44:47], v[36:39], v[10:13], 0
	ds_write2_b32 v145, v42, v54 offset0:32 offset1:48
	ds_write2_b32 v145, v43, v55 offset0:160 offset1:176
	s_nop 5
	ds_write2_b32 v144, v56, v44 offset0:64 offset1:80
	ds_write2_b32 v144, v57, v45 offset0:192 offset1:208
	ds_write2_b32 v145, v58, v46 offset0:64 offset1:80
	ds_write2_b32 v145, v59, v47 offset0:192 offset1:208
	v_mfma_f32_16x16x32_bf16 v[40:43], v[36:39], v[6:9], 0
	v_mfma_f32_16x16x32_bf16 v[36:39], v[36:39], v[2:5], 0
	s_nop 7
	ds_write2_b32 v144, v40, v36 offset0:96 offset1:112
	ds_write2_b32 v144, v41, v37 offset0:224 offset1:240
	ds_write2_b32 v145, v42, v38 offset0:96 offset1:112
	ds_write2_b32 v145, v43, v39 offset0:224 offset1:240
	s_waitcnt lgkmcnt(0)
; #define MFMA16(a, b, c) __builtin_amdgcn_mfma_f32_16x16x32_bf16((a), (b), (c), 0, 0, 0)
; DI void wave_lds_sync() { asm volatile("s_waitcnt lgkmcnt(0)" ::: "memory"); __builtin_amdgcn_wave_barrier(); }
; template <bool FINAL>
; DI void s5_item(const Params& p, int layer, int item, char* lds) {
;     ...
;     for (int nt = 0; nt < 8; ++nt) {
;       f32x4 acc = MFMA16(uf, bbf[nt], (f32x4{0.f, 0.f, 0.f, 0.f}));
; #pragma unroll
;       for (int r = 0; r < 4; ++r) bu[(quad * 4 + r) * 128 + nt * 16 + c16] = acc[r];
;     }
;     wave_lds_sync();
; #pragma unroll
;     for (int tt = 0; tt < 16; ++tt) {
;       const float br_ = bu[tt * 128 + lane], bi_ = bu[tt * 128 + 64 + lane];
	ds_read2st64_b32 v[138:139], v143 offset1:1
	ds_read2st64_b32 v[136:137], v143 offset0:2 offset1:3
	ds_read2st64_b32 v[134:135], v143 offset0:4 offset1:5
	ds_read2st64_b32 v[130:131], v143 offset0:6 offset1:7
	ds_read2st64_b32 v[126:127], v143 offset0:8 offset1:9
	ds_read2st64_b32 v[120:121], v143 offset0:10 offset1:11
	ds_read2st64_b32 v[114:115], v143 offset0:12 offset1:13
	ds_read2st64_b32 v[108:109], v143 offset0:14 offset1:15
	ds_read2st64_b32 v[102:103], v143 offset0:16 offset1:17
	ds_read2st64_b32 v[96:97], v143 offset0:18 offset1:19
	ds_read2st64_b32 v[86:87], v143 offset0:20 offset1:21
	ds_read2st64_b32 v[78:79], v143 offset0:22 offset1:23
	ds_read2st64_b32 v[72:73], v143 offset0:24 offset1:25
	ds_read2st64_b32 v[66:67], v143 offset0:26 offset1:27
	ds_read2st64_b32 v[60:61], v143 offset0:28 offset1:29
	ds_read2st64_b32 v[54:55], v143 offset0:30 offset1:31
	s_waitcnt lgkmcnt(0)
	v_mov_b32_e32 v36, 0
	v_mov_b32_e32 v37, 0
	s_waitcnt vmcnt(2)
	v_mfma_f32_16x16x32_bf16 v[38:41], v[232:235], v[30:33], 0
	v_mfma_f32_16x16x32_bf16 v[42:45], v[232:235], v[26:29], 0
	s_nop 7
	ds_write2_b32 v144, v38, v42 offset1:16
	ds_write2_b32 v144, v39, v43 offset0:128 offset1:144
	ds_write2_b32 v145, v40, v44 offset1:16
	v_mfma_f32_16x16x32_bf16 v[46:49], v[232:235], v[22:25], 0
	v_mfma_f32_16x16x32_bf16 v[50:53], v[232:235], v[18:21], 0
	ds_write2_b32 v145, v41, v45 offset0:128 offset1:144
	s_nop 6
	ds_write2_b32 v144, v46, v50 offset0:32 offset1:48
	ds_write2_b32 v144, v47, v51 offset0:160 offset1:176
	v_mfma_f32_16x16x32_bf16 v[56:59], v[232:235], v[14:17], 0
	v_mfma_f32_16x16x32_bf16 v[38:41], v[232:235], v[10:13], 0
	ds_write2_b32 v145, v48, v52 offset0:32 offset1:48
	ds_write2_b32 v145, v49, v53 offset0:160 offset1:176
	s_nop 5
	ds_write2_b32 v144, v56, v38 offset0:64 offset1:80
	ds_write2_b32 v144, v57, v39 offset0:192 offset1:208
	ds_write2_b32 v145, v58, v40 offset0:64 offset1:80
	ds_write2_b32 v145, v59, v41 offset0:192 offset1:208
	v_mfma_f32_16x16x32_bf16 v[42:45], v[232:235], v[6:9], 0
	v_mov_b32_e32 v38, 0
	v_mov_b32_e32 v39, 0
	v_mfma_f32_16x16x32_bf16 v[34:37], v[232:235], v[2:5], 0
	s_nop 7
	ds_write2_b32 v144, v42, v34 offset0:96 offset1:112
	ds_write2_b32 v144, v43, v35 offset0:224 offset1:240
	ds_write2_b32 v145, v44, v36 offset0:96 offset1:112
	ds_write2_b32 v145, v45, v37 offset0:224 offset1:240
	s_waitcnt lgkmcnt(0)
	ds_read2st64_b32 v[132:133], v143 offset1:1
	ds_read2st64_b32 v[128:129], v143 offset0:2 offset1:3
	ds_read2st64_b32 v[124:125], v143 offset0:4 offset1:5
	ds_read2st64_b32 v[118:119], v143 offset0:6 offset1:7
	ds_read2st64_b32 v[112:113], v143 offset0:8 offset1:9
	ds_read2st64_b32 v[106:107], v143 offset0:10 offset1:11
	ds_read2st64_b32 v[100:101], v143 offset0:12 offset1:13
	ds_read2st64_b32 v[92:93], v143 offset0:14 offset1:15
	ds_read2st64_b32 v[82:83], v143 offset0:16 offset1:17
	ds_read2st64_b32 v[76:77], v143 offset0:18 offset1:19
	ds_read2st64_b32 v[70:71], v143 offset0:20 offset1:21
	ds_read2st64_b32 v[64:65], v143 offset0:22 offset1:23
	ds_read2st64_b32 v[58:59], v143 offset0:24 offset1:25
	ds_read2st64_b32 v[52:53], v143 offset0:26 offset1:27
	ds_read2st64_b32 v[48:49], v143 offset0:28 offset1:29
	ds_read2st64_b32 v[44:45], v143 offset0:30 offset1:31
	s_waitcnt lgkmcnt(0)
	v_mov_b32_e32 v34, 0
	v_mov_b32_e32 v36, 0
	v_mov_b32_e32 v37, 0
	s_waitcnt vmcnt(1)
	v_mfma_f32_16x16x32_bf16 v[40:43], v[236:239], v[30:33], 0
	v_mov_b32_e32 v35, 0
	v_mfma_f32_16x16x32_bf16 v[156:159], v[236:239], v[26:29], 0
	s_nop 7
	ds_write2_b32 v144, v40, v156 offset1:16
	ds_write2_b32 v144, v41, v157 offset0:128 offset1:144
	ds_write2_b32 v145, v42, v158 offset1:16
	v_mfma_f32_16x16x32_bf16 v[160:163], v[236:239], v[22:25], 0
	v_mfma_f32_16x16x32_bf16 v[164:167], v[236:239], v[18:21], 0
	ds_write2_b32 v145, v43, v159 offset0:128 offset1:144
	s_nop 6
	ds_write2_b32 v144, v160, v164 offset0:32 offset1:48
	ds_write2_b32 v144, v161, v165 offset0:160 offset1:176
	v_mfma_f32_16x16x32_bf16 v[168:171], v[236:239], v[14:17], 0
	v_mfma_f32_16x16x32_bf16 v[40:43], v[236:239], v[10:13], 0
	ds_write2_b32 v145, v162, v166 offset0:32 offset1:48
	ds_write2_b32 v145, v163, v167 offset0:160 offset1:176
	s_nop 5
	ds_write2_b32 v144, v168, v40 offset0:64 offset1:80
	ds_write2_b32 v144, v169, v41 offset0:192 offset1:208
	ds_write2_b32 v145, v170, v42 offset0:64 offset1:80
	ds_write2_b32 v145, v171, v43 offset0:192 offset1:208
	v_mfma_f32_16x16x32_bf16 v[156:159], v[236:239], v[6:9], 0
	v_mfma_f32_16x16x32_bf16 v[36:39], v[236:239], v[2:5], 0
	s_nop 7
	ds_write2_b32 v144, v156, v36 offset0:96 offset1:112
	ds_write2_b32 v144, v157, v37 offset0:224 offset1:240
	ds_write2_b32 v145, v158, v38 offset0:96 offset1:112
	ds_write2_b32 v145, v159, v39 offset0:224 offset1:240
	s_waitcnt lgkmcnt(0)
	ds_read2st64_b32 v[122:123], v143 offset1:1
	ds_read2st64_b32 v[116:117], v143 offset0:2 offset1:3
	ds_read2st64_b32 v[110:111], v143 offset0:4 offset1:5
	ds_read2st64_b32 v[104:105], v143 offset0:6 offset1:7
	ds_read2st64_b32 v[98:99], v143 offset0:8 offset1:9
	ds_read2st64_b32 v[88:89], v143 offset0:10 offset1:11
	ds_read2st64_b32 v[80:81], v143 offset0:12 offset1:13
	ds_read2st64_b32 v[74:75], v143 offset0:14 offset1:15
	ds_read2st64_b32 v[68:69], v143 offset0:16 offset1:17
	ds_read2st64_b32 v[62:63], v143 offset0:18 offset1:19
	ds_read2st64_b32 v[56:57], v143 offset0:20 offset1:21
	ds_read2st64_b32 v[50:51], v143 offset0:22 offset1:23
	ds_read2st64_b32 v[46:47], v143 offset0:24 offset1:25
	ds_read2st64_b32 v[42:43], v143 offset0:26 offset1:27
	ds_read2st64_b32 v[40:41], v143 offset0:28 offset1:29
	ds_read2st64_b32 v[38:39], v143 offset0:30 offset1:31
	s_waitcnt lgkmcnt(0)
; template <bool FINAL>
; DI void s5_item(const Params& p, int layer, int item, char* lds) {
;     ...
;     for (int tt = 0; tt < 16; ++tt) {
;       const float br_ = bu[tt * 128 + lane], bi_ = bu[tt * 128 + 64 + lane];
;       const float nr = are * xr - aim * xi + br_;
;       const float ni = are * xi + aim * xr + bi_;
;       xr = nr; xi = ni;
	v_mov_b32_e32 v36, 0
	v_mov_b32_e32 v37, 0
	v_mul_f32_e32 v84, 0, v142
	v_fma_f32 v85, 0, v141, v84
	s_waitcnt lgkmcnt(14)
	v_add_f32_e32 v85, v85, v139
	v_fma_f32 v84, v141, 0, -v84
	v_mul_f32_e32 v90, v141, v85
	v_add_f32_e32 v84, v84, v138
	v_mul_f32_e32 v85, v142, v85
	v_fmac_f32_e32 v90, v142, v84
	v_fma_f32 v84, v141, v84, -v85
	v_add_f32_e32 v84, v136, v84
	v_add_f32_e32 v90, v137, v90
	v_mul_f32_e32 v85, v142, v84
	v_fmac_f32_e32 v85, v141, v90
	v_mul_f32_e32 v90, v142, v90
	v_fma_f32 v84, v141, v84, -v90
	v_add_f32_e32 v84, v134, v84
	v_add_f32_e32 v85, v135, v85
	v_mul_f32_e32 v90, v142, v84
	v_fmac_f32_e32 v90, v141, v85
	v_mul_f32_e32 v85, v142, v85
	v_fma_f32 v84, v141, v84, -v85
	v_add_f32_e32 v84, v130, v84
	v_add_f32_e32 v90, v131, v90
	v_mul_f32_e32 v85, v142, v84
	v_fmac_f32_e32 v85, v141, v90
	v_mul_f32_e32 v90, v142, v90
	v_fma_f32 v84, v141, v84, -v90
	v_add_f32_e32 v84, v126, v84
	v_add_f32_e32 v85, v127, v85
	v_mul_f32_e32 v90, v142, v84
	v_fmac_f32_e32 v90, v141, v85
	v_mul_f32_e32 v85, v142, v85
	v_fma_f32 v84, v141, v84, -v85
	v_add_f32_e32 v84, v120, v84
	v_add_f32_e32 v90, v121, v90
	v_mul_f32_e32 v85, v142, v84
	v_fmac_f32_e32 v85, v141, v90
	v_mul_f32_e32 v90, v142, v90
	v_fma_f32 v84, v141, v84, -v90
	v_add_f32_e32 v84, v114, v84
	v_add_f32_e32 v85, v115, v85
	v_mul_f32_e32 v90, v142, v84
	v_fmac_f32_e32 v90, v141, v85
	v_mul_f32_e32 v85, v142, v85
	v_fma_f32 v84, v141, v84, -v85
	v_add_f32_e32 v84, v108, v84
	v_add_f32_e32 v90, v109, v90
	v_mul_f32_e32 v85, v142, v84
	v_fmac_f32_e32 v85, v141, v90
	v_mul_f32_e32 v90, v142, v90
	v_fma_f32 v84, v141, v84, -v90
	v_add_f32_e32 v84, v102, v84
	v_add_f32_e32 v85, v103, v85
	v_mul_f32_e32 v90, v142, v84
	v_fmac_f32_e32 v90, v141, v85
	v_mul_f32_e32 v85, v142, v85
	v_fma_f32 v84, v141, v84, -v85
	v_add_f32_e32 v84, v96, v84
	v_add_f32_e32 v90, v97, v90
	v_mul_f32_e32 v85, v142, v84
	v_fmac_f32_e32 v85, v141, v90
	v_add_f32_e32 v85, v87, v85
	v_mul_f32_e32 v87, v142, v90
	v_fma_f32 v84, v141, v84, -v87
	v_add_f32_e32 v84, v86, v84
	v_mul_f32_e32 v86, v142, v84
	v_fmac_f32_e32 v86, v141, v85
	v_mul_f32_e32 v85, v142, v85
	v_fma_f32 v84, v141, v84, -v85
	v_add_f32_e32 v78, v78, v84
	v_add_f32_e32 v79, v79, v86
	v_mul_f32_e32 v84, v142, v78
	v_fmac_f32_e32 v84, v141, v79
	v_mul_f32_e32 v79, v142, v79
	v_fma_f32 v78, v141, v78, -v79
	v_add_f32_e32 v72, v72, v78
	v_add_f32_e32 v73, v73, v84
	v_mul_f32_e32 v78, v142, v72
	v_fmac_f32_e32 v78, v141, v73
	v_mul_f32_e32 v73, v142, v73
	v_fma_f32 v72, v141, v72, -v73
	v_add_f32_e32 v66, v66, v72
	v_add_f32_e32 v67, v67, v78
	v_mul_f32_e32 v72, v142, v66
	v_fmac_f32_e32 v72, v141, v67
	v_mul_f32_e32 v67, v142, v67
	v_fma_f32 v66, v141, v66, -v67
	v_add_f32_e32 v60, v60, v66
	v_add_f32_e32 v61, v61, v72
	v_mul_f32_e32 v66, v142, v60
	v_fmac_f32_e32 v66, v141, v61
	v_mul_f32_e32 v61, v142, v61
	v_fma_f32 v60, v141, v60, -v61
	v_add_f32_e32 v54, v54, v60
	v_add_f32_e32 v55, v55, v66
	v_mul_f32_e32 v60, v142, v54
	v_fmac_f32_e32 v60, v141, v55
	v_mul_f32_e32 v55, v142, v55
	v_add_f32_e32 v60, v60, v133
	v_fma_f32 v54, v141, v54, -v55
	v_mul_f32_e32 v61, v141, v60
	v_add_f32_e32 v54, v54, v132
	v_mul_f32_e32 v60, v142, v60
	v_fmac_f32_e32 v61, v142, v54
	v_fma_f32 v54, v141, v54, -v60
	v_add_f32_e32 v54, v128, v54
	v_add_f32_e32 v55, v129, v61
	v_mul_f32_e32 v60, v142, v54
	v_fmac_f32_e32 v60, v141, v55
	v_mul_f32_e32 v55, v142, v55
	v_fma_f32 v54, v141, v54, -v55
	v_add_f32_e32 v54, v124, v54
	v_add_f32_e32 v60, v125, v60
	v_mul_f32_e32 v55, v142, v54
	v_fmac_f32_e32 v55, v141, v60
	v_mul_f32_e32 v60, v142, v60
	v_fma_f32 v54, v141, v54, -v60
	v_add_f32_e32 v54, v118, v54
	v_add_f32_e32 v55, v119, v55
	v_mul_f32_e32 v60, v142, v54
	v_fmac_f32_e32 v60, v141, v55
	v_mul_f32_e32 v55, v142, v55
	v_fma_f32 v54, v141, v54, -v55
	v_add_f32_e32 v54, v112, v54
	v_add_f32_e32 v60, v113, v60
	v_mul_f32_e32 v55, v142, v54
	v_fmac_f32_e32 v55, v141, v60
	v_mul_f32_e32 v60, v142, v60
	v_fma_f32 v54, v141, v54, -v60
	v_add_f32_e32 v54, v106, v54
	v_add_f32_e32 v55, v107, v55
	v_mul_f32_e32 v60, v142, v54
	v_fmac_f32_e32 v60, v141, v55
	v_mul_f32_e32 v55, v142, v55
	v_fma_f32 v54, v141, v54, -v55
	v_add_f32_e32 v54, v100, v54
	v_add_f32_e32 v60, v101, v60
	v_mul_f32_e32 v55, v142, v54
	v_fmac_f32_e32 v55, v141, v60
	v_mul_f32_e32 v60, v142, v60
	v_fma_f32 v54, v141, v54, -v60
	v_add_f32_e32 v54, v92, v54
	v_add_f32_e32 v55, v93, v55
	v_mul_f32_e32 v60, v142, v54
	v_fmac_f32_e32 v60, v141, v55
	v_mul_f32_e32 v55, v142, v55
	v_fma_f32 v54, v141, v54, -v55
	v_add_f32_e32 v54, v82, v54
	v_add_f32_e32 v60, v83, v60
	v_mul_f32_e32 v55, v142, v54
	v_fmac_f32_e32 v55, v141, v60
	v_mul_f32_e32 v60, v142, v60
	v_fma_f32 v54, v141, v54, -v60
	v_add_f32_e32 v54, v76, v54
	v_add_f32_e32 v55, v77, v55
	v_mul_f32_e32 v60, v142, v54
	v_fmac_f32_e32 v60, v141, v55
	v_mul_f32_e32 v55, v142, v55
	v_fma_f32 v54, v141, v54, -v55
	v_add_f32_e32 v54, v70, v54
	v_add_f32_e32 v60, v71, v60
	v_mul_f32_e32 v55, v142, v54
	v_fmac_f32_e32 v55, v141, v60
	v_mul_f32_e32 v60, v142, v60
	v_fma_f32 v54, v141, v54, -v60
	v_add_f32_e32 v54, v64, v54
	v_add_f32_e32 v55, v65, v55
	v_mul_f32_e32 v60, v142, v54
	v_fmac_f32_e32 v60, v141, v55
	v_mul_f32_e32 v55, v142, v55
	v_fma_f32 v54, v141, v54, -v55
	v_add_f32_e32 v54, v58, v54
	v_add_f32_e32 v59, v59, v60
	v_mul_f32_e32 v55, v142, v54
	v_fmac_f32_e32 v55, v141, v59
	v_add_f32_e32 v53, v53, v55
	v_mul_f32_e32 v55, v142, v59
	v_fma_f32 v54, v141, v54, -v55
	v_add_f32_e32 v52, v52, v54
	v_mul_f32_e32 v54, v142, v52
	v_fmac_f32_e32 v54, v141, v53
	v_mul_f32_e32 v53, v142, v53
	v_fma_f32 v52, v141, v52, -v53
	v_add_f32_e32 v48, v48, v52
	v_add_f32_e32 v49, v49, v54
	v_mul_f32_e32 v52, v142, v48
	v_fmac_f32_e32 v52, v141, v49
	v_mul_f32_e32 v49, v142, v49
	v_fma_f32 v48, v141, v48, -v49
	v_add_f32_e32 v44, v44, v48
	v_add_f32_e32 v45, v45, v52
	v_mul_f32_e32 v48, v142, v44
	v_fmac_f32_e32 v48, v141, v45
	v_mul_f32_e32 v45, v142, v45
	v_add_f32_e32 v48, v48, v123
	v_fma_f32 v44, v141, v44, -v45
	v_mul_f32_e32 v49, v141, v48
	v_add_f32_e32 v44, v44, v122
	v_mul_f32_e32 v48, v142, v48
	v_fmac_f32_e32 v49, v142, v44
	v_fma_f32 v44, v141, v44, -v48
	v_add_f32_e32 v44, v116, v44
	v_add_f32_e32 v45, v117, v49
	v_mul_f32_e32 v48, v142, v44
	v_fmac_f32_e32 v48, v141, v45
	v_mul_f32_e32 v45, v142, v45
	v_fma_f32 v44, v141, v44, -v45
	s_waitcnt lgkmcnt(13)
; #define MFMA16(a, b, c) __builtin_amdgcn_mfma_f32_16x16x32_bf16((a), (b), (c), 0, 0, 0)
; DI void wave_lds_sync() { asm volatile("s_waitcnt lgkmcnt(0)" ::: "memory"); __builtin_amdgcn_wave_barrier(); }
; template <bool FINAL>
; DI void s5_item(const Params& p, int layer, int item, char* lds) {
;     ...
;       f32x4 acc = MFMA16(uf, bbf[nt], (f32x4{0.f, 0.f, 0.f, 0.f}));
; #pragma unroll
;       for (int r = 0; r < 4; ++r) bu[(quad * 4 + r) * 128 + nt * 16 + c16] = acc[r];
;     }
;     wave_lds_sync();
; #pragma unroll
;     for (int tt = 0; tt < 16; ++tt) {
;       const float br_ = bu[tt * 128 + lane], bi_ = bu[tt * 128 + 64 + lane];
;       const float nr = are * xr - aim * xi + br_;
;       const float ni = are * xi + aim * xr + bi_;
;       xr = nr; xi = ni;
	v_add_f32_e32 v44, v110, v44
	v_add_f32_e32 v48, v111, v48
	v_mul_f32_e32 v45, v142, v44
	v_fmac_f32_e32 v45, v141, v48
	v_mul_f32_e32 v48, v142, v48
	v_fma_f32 v44, v141, v44, -v48
	s_waitcnt lgkmcnt(12)
	v_add_f32_e32 v44, v104, v44
	v_add_f32_e32 v45, v105, v45
	v_mul_f32_e32 v48, v142, v44
	v_fmac_f32_e32 v48, v141, v45
	v_mul_f32_e32 v45, v142, v45
	v_fma_f32 v44, v141, v44, -v45
	s_waitcnt lgkmcnt(11)
	v_add_f32_e32 v44, v98, v44
	v_add_f32_e32 v48, v99, v48
	v_mul_f32_e32 v45, v142, v44
	v_fmac_f32_e32 v45, v141, v48
	v_mul_f32_e32 v48, v142, v48
	v_fma_f32 v44, v141, v44, -v48
	s_waitcnt lgkmcnt(10)
	v_add_f32_e32 v44, v88, v44
	v_add_f32_e32 v45, v89, v45
	v_mul_f32_e32 v48, v142, v44
	v_fmac_f32_e32 v48, v141, v45
	v_mul_f32_e32 v45, v142, v45
	v_fma_f32 v44, v141, v44, -v45
	s_waitcnt lgkmcnt(9)
	v_add_f32_e32 v44, v80, v44
	v_add_f32_e32 v48, v81, v48
	v_mul_f32_e32 v45, v142, v44
	v_fmac_f32_e32 v45, v141, v48
	v_mul_f32_e32 v48, v142, v48
	v_fma_f32 v44, v141, v44, -v48
	s_waitcnt lgkmcnt(8)
	v_add_f32_e32 v44, v74, v44
	v_add_f32_e32 v45, v75, v45
	v_mul_f32_e32 v48, v142, v44
	v_fmac_f32_e32 v48, v141, v45
	v_mul_f32_e32 v45, v142, v45
	v_fma_f32 v44, v141, v44, -v45
	s_waitcnt lgkmcnt(7)
	v_add_f32_e32 v44, v68, v44
	v_add_f32_e32 v48, v69, v48
	v_mul_f32_e32 v45, v142, v44
	v_fmac_f32_e32 v45, v141, v48
	v_mul_f32_e32 v48, v142, v48
	v_fma_f32 v44, v141, v44, -v48
	s_waitcnt lgkmcnt(6)
	v_add_f32_e32 v44, v62, v44
	v_add_f32_e32 v45, v63, v45
	v_mul_f32_e32 v48, v142, v44
	v_fmac_f32_e32 v48, v141, v45
	v_mul_f32_e32 v45, v142, v45
	v_fma_f32 v44, v141, v44, -v45
	s_waitcnt lgkmcnt(5)
	v_add_f32_e32 v44, v56, v44
	v_add_f32_e32 v48, v57, v48
	v_mul_f32_e32 v45, v142, v44
	v_fmac_f32_e32 v45, v141, v48
	v_mul_f32_e32 v48, v142, v48
	v_fma_f32 v44, v141, v44, -v48
	s_waitcnt lgkmcnt(4)
	v_add_f32_e32 v44, v50, v44
	v_add_f32_e32 v45, v51, v45
	v_mul_f32_e32 v48, v142, v44
	v_fmac_f32_e32 v48, v141, v45
	v_mul_f32_e32 v45, v142, v45
	v_fma_f32 v44, v141, v44, -v45
	s_waitcnt lgkmcnt(3)
	v_add_f32_e32 v44, v46, v44
	v_add_f32_e32 v47, v47, v48
	v_mul_f32_e32 v45, v142, v44
	v_fmac_f32_e32 v45, v141, v47
	s_waitcnt lgkmcnt(2)
	v_add_f32_e32 v43, v43, v45
	v_mul_f32_e32 v45, v142, v47
	v_fma_f32 v44, v141, v44, -v45
	v_add_f32_e32 v42, v42, v44
	s_waitcnt vmcnt(0)
	v_mfma_f32_16x16x32_bf16 v[30:33], v[240:243], v[30:33], 0
	v_mul_f32_e32 v44, v142, v42
	v_fmac_f32_e32 v44, v141, v43
	v_mul_f32_e32 v43, v142, v43
	v_mfma_f32_16x16x32_bf16 v[26:29], v[240:243], v[26:29], 0
	v_fma_f32 v42, v141, v42, -v43
	s_waitcnt lgkmcnt(1)
	v_add_f32_e32 v40, v40, v42
	s_nop 4
	ds_write2_b32 v144, v30, v26 offset1:16
	ds_write2_b32 v144, v31, v27 offset0:128 offset1:144
	ds_write2_b32 v145, v32, v28 offset1:16
	v_mfma_f32_16x16x32_bf16 v[22:25], v[240:243], v[22:25], 0
	v_add_f32_e32 v41, v41, v44
	v_mul_f32_e32 v42, v142, v40
	v_fmac_f32_e32 v42, v141, v41
	v_mfma_f32_16x16x32_bf16 v[18:21], v[240:243], v[18:21], 0
	ds_write2_b32 v145, v33, v29 offset0:128 offset1:144
	s_nop 6
	ds_write2_b32 v144, v22, v18 offset0:32 offset1:48
	ds_write2_b32 v144, v23, v19 offset0:160 offset1:176
	v_mfma_f32_16x16x32_bf16 v[14:17], v[240:243], v[14:17], 0
	v_mul_f32_e32 v41, v142, v41
	s_waitcnt lgkmcnt(6)
	v_add_f32_e32 v39, v39, v42
	v_fma_f32 v40, v141, v40, -v41
	v_mfma_f32_16x16x32_bf16 v[10:13], v[240:243], v[10:13], 0
	ds_write2_b32 v145, v24, v20 offset0:32 offset1:48
	ds_write2_b32 v145, v25, v21 offset0:160 offset1:176
	s_nop 5
	ds_write2_b32 v144, v14, v10 offset0:64 offset1:80
	ds_write2_b32 v144, v15, v11 offset0:192 offset1:208
	ds_write2_b32 v145, v16, v12 offset0:64 offset1:80
	ds_write2_b32 v145, v17, v13 offset0:192 offset1:208
	v_mfma_f32_16x16x32_bf16 v[6:9], v[240:243], v[6:9], 0
	v_add_f32_e32 v38, v38, v40
	s_lshl_b32 s0, s24, 12
	v_readlane_b32 s80, v230, 42
	v_mfma_f32_16x16x32_bf16 v[2:5], v[240:243], v[2:5], 0
	s_nop 7
	ds_write2_b32 v144, v6, v2 offset0:96 offset1:112
	ds_write2_b32 v144, v7, v3 offset0:224 offset1:240
	ds_write2_b32 v145, v8, v4 offset0:96 offset1:112
	ds_write2_b32 v145, v9, v5 offset0:224 offset1:240
	s_waitcnt lgkmcnt(0)
	ds_read2st64_b32 v[2:3], v143 offset1:1
	v_mul_f32_e32 v4, v142, v39
	v_fma_f32 v10, v141, v38, -v4
	ds_read2st64_b32 v[4:5], v143 offset0:2 offset1:3
	ds_read2st64_b32 v[6:7], v143 offset0:4 offset1:5
	ds_read2st64_b32 v[8:9], v143 offset0:6 offset1:7
	v_readlane_b32 s88, v230, 50
	s_waitcnt lgkmcnt(3)
; template <bool FINAL>
; DI void s5_item(const Params& p, int layer, int item, char* lds) {
;     ...
;     for (int tt = 0; tt < 16; ++tt) {
;       const float br_ = bu[tt * 128 + lane], bi_ = bu[tt * 128 + 64 + lane];
;       const float nr = are * xr - aim * xi + br_;
;       const float ni = are * xi + aim * xr + bi_;
;       xr = nr; xi = ni;
;     ...
;   if constexpr (!FINAL) { stp[c * 128] = xr; stp[c * 128 + 64] = xi; }
	v_add_f32_e32 v2, v10, v2
	v_mul_f32_e32 v10, v142, v38
	v_fmac_f32_e32 v10, v141, v39
	v_add_f32_e32 v3, v10, v3
	v_mul_f32_e32 v10, v142, v3
	v_mul_f32_e32 v3, v141, v3
	v_fmac_f32_e32 v3, v142, v2
	v_fma_f32 v10, v141, v2, -v10
	s_waitcnt lgkmcnt(2)
	v_add_f32_e32 v2, v5, v3
	v_add_f32_e32 v4, v4, v10
	v_mul_f32_e32 v3, v142, v2
	v_fma_f32 v3, v141, v4, -v3
	v_mul_f32_e32 v4, v142, v4
	v_fmac_f32_e32 v4, v141, v2
	s_waitcnt lgkmcnt(1)
	v_add_f32_e32 v2, v7, v4
	v_add_f32_e32 v3, v6, v3
	v_mul_f32_e32 v4, v142, v2
	v_fma_f32 v4, v141, v3, -v4
	v_mul_f32_e32 v3, v142, v3
	v_fmac_f32_e32 v3, v141, v2
	s_waitcnt lgkmcnt(0)
	v_add_f32_e32 v11, v9, v3
	ds_read2st64_b32 v[2:3], v143 offset0:8 offset1:9
	v_add_f32_e32 v10, v8, v4
	v_mul_f32_e32 v4, v142, v11
	v_fma_f32 v12, v141, v10, -v4
	v_mul_f32_e32 v10, v142, v10
	v_fmac_f32_e32 v10, v141, v11
	s_waitcnt lgkmcnt(0)
	v_add_f32_e32 v3, v3, v10
	ds_read2st64_b32 v[4:5], v143 offset0:10 offset1:11
	ds_read2st64_b32 v[6:7], v143 offset0:12 offset1:13
	ds_read2st64_b32 v[8:9], v143 offset0:14 offset1:15
	v_add_f32_e32 v2, v2, v12
	v_mul_f32_e32 v10, v142, v3
	v_fma_f32 v10, v141, v2, -v10
	v_mul_f32_e32 v2, v142, v2
	v_fmac_f32_e32 v2, v141, v3
	s_waitcnt lgkmcnt(2)
	v_add_f32_e32 v2, v5, v2
	v_add_f32_e32 v4, v4, v10
	v_mul_f32_e32 v3, v142, v2
	v_fma_f32 v3, v141, v4, -v3
	v_mul_f32_e32 v4, v142, v4
	v_fmac_f32_e32 v4, v141, v2
	s_waitcnt lgkmcnt(1)
	v_add_f32_e32 v2, v7, v4
	v_add_f32_e32 v3, v6, v3
	v_mul_f32_e32 v4, v142, v2
	v_fma_f32 v4, v141, v3, -v4
	v_mul_f32_e32 v3, v142, v3
	v_fmac_f32_e32 v3, v141, v2
	s_waitcnt lgkmcnt(0)
	v_add_f32_e32 v11, v9, v3
	ds_read2st64_b32 v[2:3], v143 offset0:16 offset1:17
	v_add_f32_e32 v10, v8, v4
	v_mul_f32_e32 v4, v142, v11
	v_fma_f32 v12, v141, v10, -v4
	v_mul_f32_e32 v10, v142, v10
	v_fmac_f32_e32 v10, v141, v11
	s_waitcnt lgkmcnt(0)
	v_add_f32_e32 v3, v3, v10
	ds_read2st64_b32 v[4:5], v143 offset0:18 offset1:19
	ds_read2st64_b32 v[6:7], v143 offset0:20 offset1:21
	ds_read2st64_b32 v[8:9], v143 offset0:22 offset1:23
	v_add_f32_e32 v2, v2, v12
	v_mul_f32_e32 v10, v142, v3
	v_fma_f32 v10, v141, v2, -v10
	v_mul_f32_e32 v2, v142, v2
	v_fmac_f32_e32 v2, v141, v3
	s_waitcnt lgkmcnt(2)
	v_add_f32_e32 v2, v5, v2
	v_add_f32_e32 v4, v4, v10
	v_mul_f32_e32 v3, v142, v2
	v_fma_f32 v3, v141, v4, -v3
	v_mul_f32_e32 v4, v142, v4
	v_fmac_f32_e32 v4, v141, v2
	s_waitcnt lgkmcnt(1)
	v_add_f32_e32 v2, v7, v4
	v_add_f32_e32 v3, v6, v3
	v_mul_f32_e32 v4, v142, v2
	v_fma_f32 v4, v141, v3, -v4
	v_mul_f32_e32 v3, v142, v3
	v_fmac_f32_e32 v3, v141, v2
	s_waitcnt lgkmcnt(0)
	v_add_f32_e32 v11, v9, v3
	ds_read2st64_b32 v[2:3], v143 offset0:24 offset1:25
	v_add_f32_e32 v10, v8, v4
	v_mul_f32_e32 v4, v142, v11
	v_fma_f32 v12, v141, v10, -v4
	v_mul_f32_e32 v10, v142, v10
	v_fmac_f32_e32 v10, v141, v11
	s_waitcnt lgkmcnt(0)
	v_add_f32_e32 v3, v3, v10
	ds_read2st64_b32 v[4:5], v143 offset0:26 offset1:27
	ds_read2st64_b32 v[6:7], v143 offset0:28 offset1:29
	ds_read2st64_b32 v[8:9], v143 offset0:30 offset1:31
	v_add_f32_e32 v2, v2, v12
	v_mul_f32_e32 v10, v142, v3
	v_fma_f32 v10, v141, v2, -v10
	v_mul_f32_e32 v2, v142, v2
	v_fmac_f32_e32 v2, v141, v3
	s_waitcnt lgkmcnt(2)
	v_add_f32_e32 v2, v5, v2
	v_add_f32_e32 v4, v4, v10
	v_mul_f32_e32 v3, v142, v2
	v_fma_f32 v3, v141, v4, -v3
	v_mul_f32_e32 v4, v142, v4
	v_fmac_f32_e32 v4, v141, v2
	s_waitcnt lgkmcnt(1)
	v_add_f32_e32 v2, v7, v4
	v_add_f32_e32 v3, v6, v3
	v_mul_f32_e32 v4, v142, v2
	v_fma_f32 v4, v141, v3, -v4
	v_mul_f32_e32 v3, v142, v3
	v_fmac_f32_e32 v3, v141, v2
	v_lshl_add_u32 v2, v140, 7, s0
	s_waitcnt lgkmcnt(0)
	v_add_f32_e32 v5, v9, v3
	v_ashrrev_i32_e32 v3, 31, v2
	v_lshlrev_b64 v[2:3], 9, v[2:3]
	v_readlane_b32 s89, v230, 51
	s_waitcnt lgkmcnt(0)
	s_lshl_b32 s64, s23, 9
	v_add_f32_e32 v4, v8, v4
	v_lshl_add_u64 v[2:3], s[88:89], 0, v[2:3]
	v_lshl_add_u64 v[2:3], v[2:3], 0, v[0:1]
	v_lshl_add_u64 v[2:3], v[2:3], 0, s[64:65]
	s_mov_b64 s[0:1], 0
	v_readlane_b32 s81, v230, 43
	v_readlane_b32 s82, v230, 44
	v_readlane_b32 s83, v230, 45
	v_readlane_b32 s84, v230, 46
	v_readlane_b32 s85, v230, 47
	v_readlane_b32 s86, v230, 48
	v_readlane_b32 s87, v230, 49
	v_readlane_b32 s90, v230, 52
	v_readlane_b32 s91, v230, 53
	v_readlane_b32 s92, v230, 54
	v_readlane_b32 s93, v230, 55
	v_readlane_b32 s94, v230, 56
	v_readlane_b32 s95, v230, 57
	global_store_dword v[2:3], v4, off
	global_store_dword v[2:3], v5, off offset:256

; DI void diff_attn_item(const Params& p, int layer, int qb, int bh, char* lds) {
;     ...
; #pragma unroll
;       for (int qt = 0; qt < 2; ++qt) {
;         float v = -1e30f;
; #pragma unroll
;         for (int ksub = 0; ksub < 4; ++ksub)
; #pragma unroll
;           for (int r = 0; r < 4; ++r) v = fmaxf(v, S[ksub][qt][r]);
;         v = quadmax(v);
;         mx[qt] = v;
;         need = need || (v > 8.f);
;       }
;       if (__any(need) || kt == 0) {
; #pragma unroll
;         for (int qt = 0; qt < 2; ++qt) {
;           const float delta = (kt == 0) ? mx[qt] : fmaxf(mx[qt], 0.f);
;           const float alpha = (kt == 0) ? 1.f : __builtin_amdgcn_exp2f(-delta);
;           m[qt] += delta;
;           l[qt] *= alpha;
; #pragma unroll
;           for (int d = 0; d < 8; ++d) O[d][qt] *= alpha;
; #pragma unroll
;           for (int ksub = 0; ksub < 4; ++ksub)
; #pragma unroll
;             for (int r = 0; r < 4; ++r) S[ksub][qt][r] -= delta;
;         }
.LBB0_1275:
	s_or_b64 exec, exec, s[72:73]
	v_max3_f32 v205, v140, s96, v141
	v_max3_f32 v204, v128, s96, v129
	v_max3_f32 v205, v205, v142, v143
	v_max3_f32 v204, v204, v130, v131
	v_max3_f32 v205, v205, v136, v137
	v_max3_f32 v204, v204, v120, v121
	v_max3_f32 v205, v205, v138, v139
	v_max3_f32 v204, v204, v122, v123
	v_max3_f32 v205, v205, v132, v133
	v_max3_f32 v204, v204, v116, v117
	v_max3_f32 v205, v205, v134, v135
	v_max3_f32 v204, v204, v118, v119
	v_max3_f32 v205, v205, v144, v145
	v_max3_f32 v204, v204, v124, v125
	v_max3_f32 v205, v205, v146, v147
	v_max3_f32 v204, v204, v126, v127
	v_max_f32_e32 v206, v205, v204
	v_cmp_lt_f32_e32 vcc, s31, v206
	s_cbranch_vccz .LBB0_1268
	v_mov_b32_e32 v206, v205
	s_nop 1
	v_permlane16_swap_b32_e32 v205, v206
	v_max_f32_e32 v205, v205, v206
	v_mov_b32_e32 v206, v205
	s_nop 1
	v_permlane32_swap_b32_e32 v205, v206
	v_max_f32_e32 v205, v205, v206
	v_mov_b32_e32 v206, v204
	s_nop 1
	v_permlane16_swap_b32_e32 v204, v206
	v_max_f32_e32 v204, v204, v206
	v_mov_b32_e32 v206, v204
	s_nop 1
	v_permlane32_swap_b32_e32 v204, v206
	v_max_f32_e32 v204, v204, v206
	v_max_f32_e32 v205, v205, v205
	v_max_f32_e32 v206, 0, v205
	v_exp_f32_e64 v208, -v206
	v_max_f32_e32 v204, v204, v204
	v_pk_add_f32 v[140:141], v[140:141], v[206:207] op_sel_hi:[1,0] neg_lo:[0,1] neg_hi:[0,1]
	v_pk_add_f32 v[142:143], v[142:143], v[206:207] op_sel_hi:[1,0] neg_lo:[0,1] neg_hi:[0,1]
	v_pk_add_f32 v[136:137], v[136:137], v[206:207] op_sel_hi:[1,0] neg_lo:[0,1] neg_hi:[0,1]
	v_pk_add_f32 v[138:139], v[138:139], v[206:207] op_sel_hi:[1,0] neg_lo:[0,1] neg_hi:[0,1]
	v_pk_add_f32 v[132:133], v[132:133], v[206:207] op_sel_hi:[1,0] neg_lo:[0,1] neg_hi:[0,1]
	v_pk_add_f32 v[134:135], v[134:135], v[206:207] op_sel_hi:[1,0] neg_lo:[0,1] neg_hi:[0,1]
	v_pk_add_f32 v[144:145], v[144:145], v[206:207] op_sel_hi:[1,0] neg_lo:[0,1] neg_hi:[0,1]
	v_pk_add_f32 v[146:147], v[146:147], v[206:207] op_sel_hi:[1,0] neg_lo:[0,1] neg_hi:[0,1]
	v_max_f32_e32 v207, 0, v204
	v_pk_mul_f32 v[66:67], v[66:67], v[208:209] op_sel_hi:[1,0]
	v_pk_mul_f32 v[64:65], v[64:65], v[208:209] op_sel_hi:[1,0]
	v_pk_mul_f32 v[70:71], v[70:71], v[208:209] op_sel_hi:[1,0]
	v_pk_mul_f32 v[68:69], v[68:69], v[208:209] op_sel_hi:[1,0]
	v_pk_mul_f32 v[74:75], v[74:75], v[208:209] op_sel_hi:[1,0]
	v_pk_mul_f32 v[72:73], v[72:73], v[208:209] op_sel_hi:[1,0]
	v_pk_mul_f32 v[78:79], v[78:79], v[208:209] op_sel_hi:[1,0]
	v_pk_mul_f32 v[76:77], v[76:77], v[208:209] op_sel_hi:[1,0]
	v_pk_mul_f32 v[82:83], v[82:83], v[208:209] op_sel_hi:[1,0]
	v_pk_mul_f32 v[80:81], v[80:81], v[208:209] op_sel_hi:[1,0]
	v_pk_mul_f32 v[62:63], v[62:63], v[208:209] op_sel_hi:[1,0]
	v_pk_mul_f32 v[60:61], v[60:61], v[208:209] op_sel_hi:[1,0]
	v_pk_mul_f32 v[58:59], v[58:59], v[208:209] op_sel_hi:[1,0]
	v_pk_mul_f32 v[56:57], v[56:57], v[208:209] op_sel_hi:[1,0]
	v_pk_mul_f32 v[54:55], v[54:55], v[208:209] op_sel_hi:[1,0]
	v_pk_mul_f32 v[52:53], v[52:53], v[208:209] op_sel_hi:[1,0]
	v_exp_f32_e64 v209, -v207
	v_pk_add_f32 v[158:159], v[158:159], v[206:207]
	v_mov_b32_e32 v204, v209
	v_pk_mul_f32 v[34:35], v[34:35], v[204:205] op_sel_hi:[1,0]
	v_pk_mul_f32 v[32:33], v[32:33], v[204:205] op_sel_hi:[1,0]
	v_pk_mul_f32 v[30:31], v[30:31], v[204:205] op_sel_hi:[1,0]
	v_pk_mul_f32 v[28:29], v[28:29], v[204:205] op_sel_hi:[1,0]
	v_pk_mul_f32 v[26:27], v[26:27], v[204:205] op_sel_hi:[1,0]
	v_pk_mul_f32 v[24:25], v[24:25], v[204:205] op_sel_hi:[1,0]
	v_pk_mul_f32 v[22:23], v[22:23], v[204:205] op_sel_hi:[1,0]
	v_pk_mul_f32 v[20:21], v[20:21], v[204:205] op_sel_hi:[1,0]
	v_pk_mul_f32 v[18:19], v[18:19], v[204:205] op_sel_hi:[1,0]
	v_pk_mul_f32 v[16:17], v[16:17], v[204:205] op_sel_hi:[1,0]
	v_pk_mul_f32 v[14:15], v[14:15], v[204:205] op_sel_hi:[1,0]
	v_pk_mul_f32 v[12:13], v[12:13], v[204:205] op_sel_hi:[1,0]
	v_pk_mul_f32 v[10:11], v[10:11], v[204:205] op_sel_hi:[1,0]
	v_pk_mul_f32 v[8:9], v[8:9], v[204:205] op_sel_hi:[1,0]
	v_pk_mul_f32 v[6:7], v[6:7], v[204:205] op_sel_hi:[1,0]
	v_pk_mul_f32 v[4:5], v[4:5], v[204:205] op_sel_hi:[1,0]
	v_mov_b32_e32 v204, v207
	v_pk_mul_f32 v[156:157], v[156:157], v[208:209]
	v_pk_add_f32 v[128:129], v[128:129], v[204:205] op_sel_hi:[1,0] neg_lo:[0,1] neg_hi:[0,1]
	v_pk_add_f32 v[130:131], v[130:131], v[204:205] op_sel_hi:[1,0] neg_lo:[0,1] neg_hi:[0,1]
	v_pk_add_f32 v[120:121], v[120:121], v[204:205] op_sel_hi:[1,0] neg_lo:[0,1] neg_hi:[0,1]
	v_pk_add_f32 v[122:123], v[122:123], v[204:205] op_sel_hi:[1,0] neg_lo:[0,1] neg_hi:[0,1]
	v_pk_add_f32 v[116:117], v[116:117], v[204:205] op_sel_hi:[1,0] neg_lo:[0,1] neg_hi:[0,1]
	v_pk_add_f32 v[118:119], v[118:119], v[204:205] op_sel_hi:[1,0] neg_lo:[0,1] neg_hi:[0,1]
	v_pk_add_f32 v[124:125], v[124:125], v[204:205] op_sel_hi:[1,0] neg_lo:[0,1] neg_hi:[0,1]
	v_pk_add_f32 v[126:127], v[126:127], v[204:205] op_sel_hi:[1,0] neg_lo:[0,1] neg_hi:[0,1]
	s_branch .LBB0_1268

; #define MFMA16(a, b, c) __builtin_amdgcn_mfma_f32_16x16x32_bf16((a), (b), (c), 0, 0, 0)
; DI bf16_t f2bf(float x) { return (bf16_t)(pack2(x, 0.f) & 0xffffu); }
; DI float bf2f(bf16_t h) { return __uint_as_float(((unsigned)h) << 16); }
; DI void wave_lds_sync() { asm volatile("s_waitcnt lgkmcnt(0)" ::: "memory"); __builtin_amdgcn_wave_barrier(); }
; template <bool FINAL>
; DI void s5_item(const Params& p, int layer, int item, char* lds) {
;     ...
;     if (quad < 2) uf = *(const bf16x8*)(p.proj + (size_t)(tb + c16) * PW + C_AU + g * 16 + quad * 8);
;     float uo[FINAL ? 4 : 1];
;     if constexpr (FINAL) {
; #pragma unroll
;       for (int r = 0; r < 4; ++r) uo[r] = bf2f(p.proj[(size_t)(tb + quad * 4 + r) * PW + C_AU + g * 16 + c16]);
;     }
; #pragma unroll
;     for (int nt = 0; nt < 8; ++nt) {
;       f32x4 acc = MFMA16(uf, bbf[nt], (f32x4{0.f, 0.f, 0.f, 0.f}));
; #pragma unroll
;       for (int r = 0; r < 4; ++r) bu[(quad * 4 + r) * 128 + nt * 16 + c16] = acc[r];
;     }
;     wave_lds_sync();
; #pragma unroll
;     for (int tt = 0; tt < 16; ++tt) {
;       const float br_ = bu[tt * 128 + lane], bi_ = bu[tt * 128 + 64 + lane];
;       const float nr = are * xr - aim * xi + br_;
;       const float ni = are * xi + aim * xr + bi_;
;       xr = nr; xi = ni;
;       if constexpr (FINAL) {
;         *(bf16_t*)(xsb + tt * 256 + ((((lane >> 3)) ^ tt) << 4) + (lane & 7) * 2) = f2bf(xr);
;         *(bf16_t*)(xsb + tt * 256 + (((8 + (lane >> 3)) ^ tt) << 4) + (lane & 7) * 2) = f2bf(xi);
;       }
;     }
.LBB0_1300:
	s_or_b64 exec, exec, s[6:7]
	v_add_u32_e32 v0, s5, v75
	v_mov_b32_e32 v63, v1
	v_lshl_add_u64 v[68:69], v[0:1], 1, v[60:61]
	v_add_u32_e32 v62, 0x1200, v0
	v_lshl_add_u64 v[66:67], v[62:63], 1, v[60:61]
	v_add_u32_e32 v62, 0x2400, v0
	v_lshl_add_u64 v[64:65], v[62:63], 1, v[60:61]
	v_add_u32_e32 v0, 0x3600, v0
	v_lshl_add_u64 v[62:63], v[0:1], 1, v[60:61]
	global_load_ushort v236, v[68:69], off
	global_load_ushort v237, v[66:67], off
	global_load_ushort v238, v[64:65], off
	global_load_ushort v239, v[62:63], off
	s_waitcnt vmcnt(4)
	v_mfma_f32_16x16x32_bf16 v[92:95], v[50:53], v[2:5], 0
	v_add_u32_e32 v100, 0x400, v73
	s_add_i32 s5, s5, 0x12000
	s_cmp_eq_u32 s5, 0x48000
	v_mfma_f32_16x16x32_bf16 v[96:99], v[50:53], v[6:9], 0
	s_nop 7
	ds_write2_b32 v73, v92, v96 offset1:16
	ds_write2_b32 v73, v93, v97 offset0:128 offset1:144
	ds_write2_b32 v100, v94, v98 offset1:16
	ds_write2_b32 v100, v95, v99 offset0:128 offset1:144
	v_mfma_f32_16x16x32_bf16 v[92:95], v[50:53], v[10:13], 0
	s_waitcnt vmcnt(0)
	v_lshlrev_b32_e32 v91, 16, v236
	v_lshlrev_b32_e32 v90, 16, v237
	v_lshlrev_b32_e32 v89, 16, v238
	v_lshlrev_b32_e32 v0, 16, v239
	v_mfma_f32_16x16x32_bf16 v[96:99], v[50:53], v[14:17], 0
	s_nop 7
	ds_write2_b32 v73, v92, v96 offset0:32 offset1:48
	ds_write2_b32 v73, v93, v97 offset0:160 offset1:176
	ds_write2_b32 v100, v94, v98 offset0:32 offset1:48
	ds_write2_b32 v100, v95, v99 offset0:160 offset1:176
	v_mfma_f32_16x16x32_bf16 v[92:95], v[50:53], v[18:21], 0
	v_mfma_f32_16x16x32_bf16 v[96:99], v[50:53], v[22:25], 0
	s_nop 7
	ds_write2_b32 v73, v92, v96 offset0:64 offset1:80
	ds_write2_b32 v73, v93, v97 offset0:192 offset1:208
	ds_write2_b32 v100, v94, v98 offset0:64 offset1:80
	ds_write2_b32 v100, v95, v99 offset0:192 offset1:208
	v_mfma_f32_16x16x32_bf16 v[92:95], v[50:53], v[26:29], 0
	v_mfma_f32_16x16x32_bf16 v[50:53], v[50:53], v[30:33], 0
	s_nop 7
	ds_write2_b32 v73, v92, v50 offset0:96 offset1:112
	ds_write2_b32 v73, v93, v51 offset0:224 offset1:240
	ds_write2_b32 v100, v94, v52 offset0:96 offset1:112
	ds_write2_b32 v100, v95, v53 offset0:224 offset1:240
	s_waitcnt lgkmcnt(0)
	ds_read2st64_b32 v[232:233], v74 offset1:1
	ds_read2st64_b32 v[234:235], v74 offset0:2 offset1:3
	ds_read2st64_b32 v[236:237], v74 offset0:4 offset1:5
	ds_read2st64_b32 v[238:239], v74 offset0:6 offset1:7
	ds_read2st64_b32 v[240:241], v74 offset0:8 offset1:9
	ds_read2st64_b32 v[242:243], v74 offset0:10 offset1:11
	ds_read2st64_b32 v[244:245], v74 offset0:12 offset1:13
	ds_read2st64_b32 v[246:247], v74 offset0:14 offset1:15
	ds_read2st64_b32 v[248:249], v74 offset0:16 offset1:17
	ds_read2st64_b32 v[250:251], v74 offset0:18 offset1:19
	ds_read2st64_b32 v[252:253], v74 offset0:20 offset1:21
	ds_read2st64_b32 v[254:255], v74 offset0:22 offset1:23
	v_mul_f32_e32 v52, v56, v71
	v_fma_f32 v52, v54, v70, -v52
	s_waitcnt lgkmcnt(11)
	v_add_f32_e32 v52, v52, v232
	v_mul_f32_e32 v50, v54, v71
	v_fmac_f32_e32 v50, v56, v70
	v_add_f32_e32 v53, v50, v233
	v_cvt_pk_bf16_f32 v50, v52, s0
	ds_write_b16 v77, v50 offset:8192
	v_cvt_pk_bf16_f32 v51, v53, s0
	ds_write_b16 v77, v51 offset:8320
	v_mul_f32_e32 v70, v56, v53
	v_fma_f32 v70, v54, v52, -v70
	s_waitcnt lgkmcnt(12)
	v_add_f32_e32 v70, v70, v234
	v_mul_f32_e32 v50, v54, v53
	v_fmac_f32_e32 v50, v56, v52
	v_add_f32_e32 v71, v50, v235
	v_cvt_pk_bf16_f32 v50, v70, s0
	ds_write_b16 v78, v50 offset:8448
	v_cvt_pk_bf16_f32 v51, v71, s0
	ds_write_b16 v78, v51 offset:8576
	v_mul_f32_e32 v52, v56, v71
	v_fma_f32 v52, v54, v70, -v52
	s_waitcnt lgkmcnt(13)
	v_add_f32_e32 v52, v52, v236
	v_mul_f32_e32 v50, v54, v71
	v_fmac_f32_e32 v50, v56, v70
	v_add_f32_e32 v53, v50, v237
	v_cvt_pk_bf16_f32 v50, v52, s0
	ds_write_b16 v79, v50 offset:8704
	v_cvt_pk_bf16_f32 v51, v53, s0
	ds_write_b16 v79, v51 offset:8832
	v_mul_f32_e32 v70, v56, v53
	v_fma_f32 v70, v54, v52, -v70
	s_waitcnt lgkmcnt(14)
	v_add_f32_e32 v70, v70, v238
	v_mul_f32_e32 v50, v54, v53
	v_fmac_f32_e32 v50, v56, v52
	v_add_f32_e32 v71, v50, v239
	v_cvt_pk_bf16_f32 v50, v70, s0
	ds_write_b16 v80, v50 offset:8960
	v_cvt_pk_bf16_f32 v51, v71, s0
	ds_write_b16 v80, v51 offset:9088
	ds_read2st64_b32 v[232:233], v74 offset0:24 offset1:25
	ds_read2st64_b32 v[234:235], v74 offset0:26 offset1:27
	ds_read2st64_b32 v[236:237], v74 offset0:28 offset1:29
	ds_read2st64_b32 v[238:239], v74 offset0:30 offset1:31
	v_mul_f32_e32 v52, v56, v71
	v_fma_f32 v52, v54, v70, -v52
	s_waitcnt lgkmcnt(15)
	v_add_f32_e32 v52, v52, v240
	v_mul_f32_e32 v50, v54, v71
	v_fmac_f32_e32 v50, v56, v70
	v_add_f32_e32 v53, v50, v241
	v_cvt_pk_bf16_f32 v50, v52, s0
	ds_write_b16 v81, v50 offset:9216
	v_cvt_pk_bf16_f32 v51, v53, s0
	ds_write_b16 v81, v51 offset:9344
	v_mul_f32_e32 v70, v56, v53
	v_fma_f32 v70, v54, v52, -v70
	s_waitcnt lgkmcnt(15)
	v_add_f32_e32 v70, v70, v242
	v_mul_f32_e32 v50, v54, v53
	v_fmac_f32_e32 v50, v56, v52
	v_add_f32_e32 v71, v50, v243
	v_cvt_pk_bf16_f32 v50, v70, s0
	ds_write_b16 v82, v50 offset:9472
	v_cvt_pk_bf16_f32 v51, v71, s0
	ds_write_b16 v82, v51 offset:9600
	v_mul_f32_e32 v52, v56, v71
	v_fma_f32 v52, v54, v70, -v52
	s_waitcnt lgkmcnt(15)
	v_add_f32_e32 v52, v52, v244
	v_mul_f32_e32 v50, v54, v71
	v_fmac_f32_e32 v50, v56, v70
	v_add_f32_e32 v53, v50, v245
	v_cvt_pk_bf16_f32 v50, v52, s0
	ds_write_b16 v83, v50 offset:9728
	v_cvt_pk_bf16_f32 v51, v53, s0
	ds_write_b16 v83, v51 offset:9856
	v_mul_f32_e32 v70, v56, v53
	v_fma_f32 v70, v54, v52, -v70
	s_waitcnt lgkmcnt(15)
	v_add_f32_e32 v70, v70, v246
	v_mul_f32_e32 v50, v54, v53
	v_fmac_f32_e32 v50, v56, v52
	v_add_f32_e32 v71, v50, v247
	v_cvt_pk_bf16_f32 v50, v70, s0
	ds_write_b16 v84, v50 offset:9984
	v_cvt_pk_bf16_f32 v51, v71, s0
	ds_write_b16 v84, v51 offset:10112
	v_mul_f32_e32 v52, v56, v71
	v_fma_f32 v52, v54, v70, -v52
	s_waitcnt lgkmcnt(15)
; #define MFMA16(a, b, c) __builtin_amdgcn_mfma_f32_16x16x32_bf16((a), (b), (c), 0, 0, 0)
; DI bf16_t f2bf(float x) { return (bf16_t)(pack2(x, 0.f) & 0xffffu); }
; DI void wave_lds_sync() { asm volatile("s_waitcnt lgkmcnt(0)" ::: "memory"); __builtin_amdgcn_wave_barrier(); }
; template <bool FINAL>
; DI void s5_item(const Params& p, int layer, int item, char* lds) {
;     ...
;     if constexpr (FINAL) {
;       wave_lds_sync();
;       f32x4 y = f32x4{0.f, 0.f, 0.f, 0.f};
; #pragma unroll
;       for (int ks = 0; ks < 4; ++ks) {
;         const bf16x8 xf = *(const bf16x8*)(xsb + c16 * 256 + (((ks * 4 + quad) ^ c16) << 4));
;         y = MFMA16(xf, cf[ks], y);
;       }
; #pragma unroll
;       for (int r = 0; r < 4; ++r) {
;         const float v = y[r] + dsk * uo[r];
;         p.proj[(size_t)(tb + quad * 4 + r) * PW + C_AU + g * 16 + c16] = f2bf(gelu_tanh(v));
;       }
	v_add_f32_e32 v52, v52, v248
	v_mul_f32_e32 v50, v54, v71
	v_fmac_f32_e32 v50, v56, v70
	v_add_f32_e32 v53, v50, v249
	v_cvt_pk_bf16_f32 v50, v52, s0
	ds_write_b16 v77, v50 offset:10368
	v_cvt_pk_bf16_f32 v51, v53, s0
	ds_write_b16 v77, v51 offset:10240
	v_mul_f32_e32 v70, v56, v53
	v_fma_f32 v70, v54, v52, -v70
	s_waitcnt lgkmcnt(15)
	v_add_f32_e32 v70, v70, v250
	v_mul_f32_e32 v50, v54, v53
	v_fmac_f32_e32 v50, v56, v52
	v_add_f32_e32 v71, v50, v251
	v_cvt_pk_bf16_f32 v50, v70, s0
	ds_write_b16 v78, v50 offset:10624
	v_cvt_pk_bf16_f32 v51, v71, s0
	ds_write_b16 v78, v51 offset:10496
	v_mul_f32_e32 v52, v56, v71
	v_fma_f32 v52, v54, v70, -v52
	s_waitcnt lgkmcnt(15)
	v_add_f32_e32 v52, v52, v252
	v_mul_f32_e32 v50, v54, v71
	v_fmac_f32_e32 v50, v56, v70
	v_add_f32_e32 v53, v50, v253
	v_cvt_pk_bf16_f32 v50, v52, s0
	ds_write_b16 v79, v50 offset:10880
	v_cvt_pk_bf16_f32 v51, v53, s0
	ds_write_b16 v79, v51 offset:10752
	v_mul_f32_e32 v70, v56, v53
	v_fma_f32 v70, v54, v52, -v70
	s_waitcnt lgkmcnt(15)
	v_add_f32_e32 v70, v70, v254
	v_mul_f32_e32 v50, v54, v53
	v_fmac_f32_e32 v50, v56, v52
	v_add_f32_e32 v71, v50, v255
	v_cvt_pk_bf16_f32 v50, v70, s0
	ds_write_b16 v80, v50 offset:11136
	v_cvt_pk_bf16_f32 v51, v71, s0
	ds_write_b16 v80, v51 offset:11008
	v_mul_f32_e32 v52, v56, v71
	v_fma_f32 v52, v54, v70, -v52
	s_waitcnt lgkmcnt(15)
	v_add_f32_e32 v52, v52, v232
	v_mul_f32_e32 v50, v54, v71
	v_fmac_f32_e32 v50, v56, v70
	v_add_f32_e32 v53, v50, v233
	v_cvt_pk_bf16_f32 v50, v52, s0
	ds_write_b16 v81, v50 offset:11392
	v_cvt_pk_bf16_f32 v51, v53, s0
	ds_write_b16 v81, v51 offset:11264
	v_mul_f32_e32 v70, v56, v53
	v_fma_f32 v70, v54, v52, -v70
	s_waitcnt lgkmcnt(15)
	v_add_f32_e32 v70, v70, v234
	v_mul_f32_e32 v50, v54, v53
	v_fmac_f32_e32 v50, v56, v52
	v_add_f32_e32 v71, v50, v235
	v_cvt_pk_bf16_f32 v50, v70, s0
	ds_write_b16 v82, v50 offset:11648
	v_cvt_pk_bf16_f32 v51, v71, s0
	ds_write_b16 v82, v51 offset:11520
	v_mul_f32_e32 v52, v56, v71
	v_fma_f32 v52, v54, v70, -v52
	s_waitcnt lgkmcnt(15)
	v_add_f32_e32 v52, v52, v236
	v_mul_f32_e32 v50, v54, v71
	v_fmac_f32_e32 v50, v56, v70
	v_add_f32_e32 v53, v50, v237
	v_cvt_pk_bf16_f32 v50, v52, s0
	ds_write_b16 v83, v50 offset:11904
	v_cvt_pk_bf16_f32 v51, v53, s0
	ds_write_b16 v83, v51 offset:11776
	v_mul_f32_e32 v70, v56, v53
	v_fma_f32 v70, v54, v52, -v70
	s_waitcnt lgkmcnt(15)
	v_add_f32_e32 v70, v70, v238
	v_mul_f32_e32 v50, v54, v53
	v_fmac_f32_e32 v50, v56, v52
	v_add_f32_e32 v71, v50, v239
	v_cvt_pk_bf16_f32 v50, v70, s0
	ds_write_b16 v84, v50 offset:12160
	v_cvt_pk_bf16_f32 v51, v71, s0
	ds_write_b16 v84, v51 offset:12032
	s_waitcnt lgkmcnt(0)
	ds_read_b128 v[50:53], v85 offset:8192
	ds_read_b128 v[92:95], v86 offset:8192
	ds_read_b128 v[232:235], v87 offset:8192
	ds_read_b128 v[236:239], v88 offset:8192
	s_waitcnt lgkmcnt(3)
	v_mfma_f32_16x16x32_bf16 v[50:53], v[50:53], v[34:37], 0
	s_waitcnt lgkmcnt(2)
	v_mfma_f32_16x16x32_bf16 v[50:53], v[92:95], v[38:41], v[50:53]
	s_waitcnt lgkmcnt(1)
	v_mfma_f32_16x16x32_bf16 v[50:53], v[232:235], v[42:45], v[50:53]
	s_waitcnt lgkmcnt(0)
	v_mfma_f32_16x16x32_bf16 v[50:53], v[236:239], v[46:49], v[50:53]
	s_nop 7
	v_fma_f32 v50, v72, v91, v50
	v_mul_f32_e32 v91, 0x3d372713, v50
	v_mul_f32_e32 v91, v50, v91
	v_fma_f32 v91, v50, v91, v50
	v_mul_f32_e32 v91, 0x3f4c422a, v91
	v_add_f32_e32 v91, v91, v91
	v_mul_f32_e32 v91, 0x3fb8aa3b, v91
	v_exp_f32_e32 v91, v91
	v_mul_f32_e32 v50, 0.5, v50
	v_fmac_f32_e32 v53, v72, v0
	v_mul_f32_e32 v0, 0x3d372713, v53
	v_add_f32_e32 v91, 1.0, v91
	v_div_scale_f32 v92, s[6:7], v91, v91, 2.0
	v_rcp_f32_e32 v93, v92
	v_mul_f32_e32 v0, v53, v0
	v_fma_f32 v0, v53, v0, v53
	v_mul_f32_e32 v0, 0x3f4c422a, v0
	v_fma_f32 v94, -v92, v93, 1.0
	v_fmac_f32_e32 v93, v94, v93
	v_div_scale_f32 v94, vcc, 2.0, v91, 2.0
	v_mul_f32_e32 v95, v94, v93
	v_fma_f32 v96, -v92, v95, v94
	v_fmac_f32_e32 v95, v96, v93
	v_fma_f32 v92, -v92, v95, v94
	v_div_fmas_f32 v92, v92, v93, v95
	v_div_fixup_f32 v91, v92, v91, 2.0
	v_sub_f32_e32 v91, 1.0, v91
	v_add_f32_e32 v91, 1.0, v91
	v_mul_f32_e32 v50, v50, v91
	v_cvt_pk_bf16_f32 v50, v50, s0
	global_store_short v[68:69], v50, off
	v_fma_f32 v50, v72, v90, v51
	v_mul_f32_e32 v51, 0x3d372713, v50
	v_mul_f32_e32 v51, v50, v51
	v_fma_f32 v51, v50, v51, v50
	v_mul_f32_e32 v51, 0x3f4c422a, v51
	v_add_f32_e32 v51, v51, v51
	v_mul_f32_e32 v51, 0x3fb8aa3b, v51
	v_exp_f32_e32 v51, v51
	v_mul_f32_e32 v50, 0.5, v50
	v_add_f32_e32 v0, v0, v0
	v_mul_f32_e32 v0, 0x3fb8aa3b, v0
	v_add_f32_e32 v51, 1.0, v51
	v_div_scale_f32 v68, s[6:7], v51, v51, 2.0
	v_rcp_f32_e32 v69, v68
	v_exp_f32_e32 v0, v0
	v_fma_f32 v90, -v68, v69, 1.0
	v_fmac_f32_e32 v69, v90, v69
	v_div_scale_f32 v90, vcc, 2.0, v51, 2.0
	v_mul_f32_e32 v91, v90, v69
	v_fma_f32 v92, -v68, v91, v90
	v_fmac_f32_e32 v91, v92, v69
	v_fma_f32 v68, -v68, v91, v90
	v_div_fmas_f32 v68, v68, v69, v91
	v_div_fixup_f32 v51, v68, v51, 2.0
	v_sub_f32_e32 v51, 1.0, v51
	v_add_f32_e32 v51, 1.0, v51
	v_mul_f32_e32 v50, v50, v51
	v_cvt_pk_bf16_f32 v50, v50, s0
	global_store_short v[66:67], v50, off
	v_fma_f32 v50, v72, v89, v52
	v_mul_f32_e32 v51, 0x3d372713, v50
	v_mul_f32_e32 v51, v50, v51
	v_fma_f32 v51, v50, v51, v50
	v_mul_f32_e32 v51, 0x3f4c422a, v51
	v_add_f32_e32 v51, v51, v51
	v_mul_f32_e32 v51, 0x3fb8aa3b, v51
	v_exp_f32_e32 v51, v51
	v_mul_f32_e32 v50, 0.5, v50
	v_add_f32_e32 v0, 1.0, v0
	v_add_f32_e32 v51, 1.0, v51
	v_div_scale_f32 v52, s[6:7], v51, v51, 2.0
	v_rcp_f32_e32 v66, v52
	s_nop 0
	v_fma_f32 v67, -v52, v66, 1.0
	v_fmac_f32_e32 v66, v67, v66
	v_div_scale_f32 v67, vcc, 2.0, v51, 2.0
	v_mul_f32_e32 v68, v67, v66
	v_fma_f32 v69, -v52, v68, v67
	v_fmac_f32_e32 v68, v69, v66
	v_fma_f32 v52, -v52, v68, v67
	v_div_fmas_f32 v52, v52, v66, v68
	v_div_fixup_f32 v51, v52, v51, 2.0
	v_sub_f32_e32 v51, 1.0, v51
	v_add_f32_e32 v51, 1.0, v51
	v_mul_f32_e32 v50, v50, v51
	v_cvt_pk_bf16_f32 v50, v50, s0
	global_store_short v[64:65], v50, off
	v_div_scale_f32 v50, s[6:7], v0, v0, 2.0
	v_rcp_f32_e32 v51, v50
	s_nop 0
	v_fma_f32 v52, -v50, v51, 1.0
	v_fmac_f32_e32 v51, v52, v51
	v_div_scale_f32 v52, vcc, 2.0, v0, 2.0
	v_mul_f32_e32 v64, v52, v51
	v_fma_f32 v65, -v50, v64, v52
	v_fmac_f32_e32 v64, v65, v51
	v_fma_f32 v50, -v50, v64, v52
	v_div_fmas_f32 v50, v50, v51, v64
	v_div_fixup_f32 v0, v50, v0, 2.0
	v_sub_f32_e32 v0, 1.0, v0
	v_mul_f32_e32 v50, 0.5, v53
	v_add_f32_e32 v0, 1.0, v0
	v_mul_f32_e32 v0, v50, v0
	v_cvt_pk_bf16_f32 v0, v0, s0
	global_store_short v[62:63], v0, off
	s_waitcnt lgkmcnt(0)
	s_cbranch_scc1 .LBB0_1303

; __global__ void __launch_bounds__(256, 2) hymba_forward(Params p) {
	.amdhsa_kernel _Z13hymba_forward6Params
		.amdhsa_group_segment_fixed_size 16
		.amdhsa_private_segment_fixed_size 0
		.amdhsa_kernarg_size 664
		.amdhsa_user_sgpr_count 2
		.amdhsa_user_sgpr_dispatch_ptr 0
		.amdhsa_user_sgpr_queue_ptr 0
		.amdhsa_user_sgpr_kernarg_segment_ptr 1
		.amdhsa_user_sgpr_dispatch_id 0
		.amdhsa_user_sgpr_kernarg_preload_length 0
		.amdhsa_user_sgpr_kernarg_preload_offset 0
		.amdhsa_user_sgpr_private_segment_size 0
		.amdhsa_uses_dynamic_stack 0
		.amdhsa_enable_private_segment 0
		.amdhsa_system_sgpr_workgroup_id_x 1
		.amdhsa_system_sgpr_workgroup_id_y 0
		.amdhsa_system_sgpr_workgroup_id_z 0
		.amdhsa_system_sgpr_workgroup_info 0
		.amdhsa_system_vgpr_workitem_id 2
		.amdhsa_next_free_vgpr 256
		.amdhsa_next_free_sgpr 102
		.amdhsa_accum_offset 256
		.amdhsa_reserve_vcc 1
		.amdhsa_float_round_mode_32 0
		.amdhsa_float_round_mode_16_64 0
		.amdhsa_float_denorm_mode_32 3
		.amdhsa_float_denorm_mode_16_64 3
		.amdhsa_dx10_clamp 1
		.amdhsa_ieee_mode 1
		.amdhsa_fp16_overflow 0
		.amdhsa_tg_split 0
		.amdhsa_exception_fp_ieee_invalid_op 0
		.amdhsa_exception_fp_denorm_src 0
		.amdhsa_exception_fp_ieee_div_zero 0
		.amdhsa_exception_fp_ieee_overflow 0
		.amdhsa_exception_fp_ieee_underflow 0
		.amdhsa_exception_fp_ieee_inexact 0
		.amdhsa_exception_int_div_zero 0
	.end_amdhsa_kernel

; __global__ void __launch_bounds__(256, 2) hymba_forward(Params p) {
amdhsa.kernels:
  - .agpr_count:     0
    .args:
      - .offset:         0
        .size:           408
        .value_kind:     by_value
      - .offset:         408
        .size:           4
        .value_kind:     hidden_block_count_x
      - .offset:         412
        .size:           4
        .value_kind:     hidden_block_count_y
      - .offset:         416
        .size:           4
        .value_kind:     hidden_block_count_z
      - .offset:         420
        .size:           2
        .value_kind:     hidden_group_size_x
      - .offset:         422
        .size:           2
        .value_kind:     hidden_group_size_y
      - .offset:         424
        .size:           2
        .value_kind:     hidden_group_size_z
      - .offset:         426
        .size:           2
        .value_kind:     hidden_remainder_x
      - .offset:         428
        .size:           2
        .value_kind:     hidden_remainder_y
      - .offset:         430
        .size:           2
        .value_kind:     hidden_remainder_z
      - .offset:         448
        .size:           8
        .value_kind:     hidden_global_offset_x
      - .offset:         456
        .size:           8
        .value_kind:     hidden_global_offset_y
      - .offset:         464
        .size:           8
        .value_kind:     hidden_global_offset_z
      - .offset:         472
        .size:           2
        .value_kind:     hidden_grid_dims
      - .offset:         496
        .size:           8
        .value_kind:     hidden_multigrid_sync_arg
      - .offset:         528
        .size:           4
        .value_kind:     hidden_dynamic_lds_size
    .group_segment_fixed_size: 16
    .kernarg_segment_align: 8
    .kernarg_segment_size: 664
    .language:       OpenCL C
    .language_version:
      - 2
      - 0
    .max_flat_workgroup_size: 256
    .name:           _Z13hymba_forward6Params
    .private_segment_fixed_size: 0
    .sgpr_count:     108
    .sgpr_spill_count: 209
    .symbol:         _Z13hymba_forward6Params.kd
    .uniform_work_group_size: 1
    .uses_dynamic_stack: false
    .vgpr_count:     256
    .vgpr_spill_count: 0
    .wavefront_size: 64
